# adds two-pass ordering of the workgroup attention classes (large halves of dif/fox/nsa first)
# baseline (speedup 1.0000x reference)
; #define LAS __attribute__((address_space(3)))
; __device__ __forceinline__ unsigned xb_xcc_id() { return (unsigned)__builtin_amdgcn_s_getreg((3 << 11) | 20) & 0xFu; }
; #define WG_DRAW(cls, q) LAS int* slot = (LAS int*)(lds + MISC_OFF + 64); \
;         if (threadIdx.x == 0) *slot = (int)__hip_atomic_fetch_add(XQ_HEAD(cls, q), 1u, RLX_AGENT); \
;         __syncthreads(); const int it = *slot; __syncthreads();
; template <int ATTM> __device__ __forceinline__ void attention_phase(int layer, int lane, int rep, LAS unsigned char* lds, int wave) {
;     asm volatile("" : "+s"(wave));
;     ...
;     if ((ATTM & 2) && PK(2)) {
; #pragma unroll 1
;         for (int qq = 0; qq < 8; ++qq) { const int q = ((int)(xb_xcc_id() & 7u) + qq) & 7;
;             for (;;) { WG_DRAW(0, q); if (it >= 32) break;
.LBB0_544:
	s_mov_b32 s101, 0
	s_load_dwordx2 s[12:13], s[0:1], 0x98
	v_and_b32_e32 v5, 7, v239
	v_lshlrev_b32_e32 v5, 8, v5
	v_add_u32_e32 v5, 0x4400, v5
	s_waitcnt lgkmcnt(0)
	global_load_dword v6, v5, s[12:13] sc1
	s_waitcnt vmcnt(0)
	v_cmp_ne_u32_e32 vcc, 0, v6
	s_nop 1
	s_and_b32 s100, vcc_lo, 0xff
	s_cmp_eq_u32 s100, 0xff
	s_cselect_b32 s100, 1, 8
	s_cmp_le_i32 s68, s4
	s_cselect_b64 s[2:3], -1, 0
	s_and_b64 s[4:5], s[2:3], s[14:15]
	s_mov_b64 s[2:3], -1
	s_and_b64 vcc, exec, s[4:5]
	s_cbranch_vccnz .LBB0_546
	v_readlane_b32 s2, v255, 20
	s_add_i32 s4, s2, 6
	s_mov_b64 s[2:3], 0

; __device__ __forceinline__ float wave_sum(float v) { v += lx<1>(v); v += lx<2>(v); v += lx<4>(v); v += lx<8>(v); v += lx<16>(v); return half_sum(v); }
; #define ARG_IN(i) ((const float*)karg64(8 * (i)))
; #define ARG_WS() ((unsigned char*)karg64(8 * 19))
; template <int ATTM> __device__ __forceinline__ void attention_phase(int layer, int lane, int rep, LAS unsigned char* lds, int wave) {
;     ...
;                 unsigned char* ws = ARG_WS(); int tid = threadIdx.x; asm volatile("" : "+v"(tid));
;                 const float* lamv = ARG_IN(A_LAM) + (size_t)layer * 4 * 64;
;                 const float lam_init = 0.8f - 0.6f * __builtin_amdgcn_exp2f(-0.3f * 1.4426950408889634f * (float)layer);
;                 const float sa = wave_sum(lamv[lane] * lamv[64 + lane]), sb = wave_sum(lamv[128 + lane] * lamv[192 + lane]);
;                 const float lam = __builtin_amdgcn_exp2f(1.4426950408889634f * sa) - __builtin_amdgcn_exp2f(1.4426950408889634f * sb) + lam_init;
;                 dif_coop(WSP(bf16, WS_PROJ), ws + WS_VTB, WSP(bf16, WS_O), lam, ARG_IN(A_SUBG) + (size_t)layer * 128, 1.f - lam_init, q, 31 - it, lds, tid); } } }
.Lmy_att_preamble:
	v_readlane_b32 s6, v255, 21
	s_load_dword s4, s[72:73], 0x0
	v_mov_b32_e32 v4, v0
	v_cvt_f32_u32_e32 v1, s6
	v_mov_b32_e32 v2, 0x3f4ccccd
	s_waitcnt lgkmcnt(0)
	v_mul_f32_e32 v1, 0xbedd9914, v1
	v_exp_f32_e32 v1, v1
	v_readlane_b32 s7, v255, 22
	v_readfirstlane_b32 s4, v4
	s_mul_i32 s33, s6, 40
	v_fmamk_f32 v1, v1, 0xbf19999a, v2
	v_and_b32_e32 v2, 63, v4
	s_lshl_b64 s[2:3], s[6:7], 10
	s_lshl_b64 s[72:73], s[6:7], 9
	s_waitcnt vmcnt(0)
	v_sub_f32_e32 v182, 1.0, v1
	s_ashr_i32 s94, s4, 6
	s_mov_b32 s6, 0
	v_lshlrev_b32_e32 v172, 2, v2
	s_branch .LBB0_549

; #define WG_DRAW(cls, q) LAS int* slot = (LAS int*)(lds + MISC_OFF + 64); \
;         if (threadIdx.x == 0) *slot = (int)__hip_atomic_fetch_add(XQ_HEAD(cls, q), 1u, RLX_AGENT); \
;         __syncthreads(); const int it = *slot; __syncthreads();
; template <int ATTM> __device__ __forceinline__ void attention_phase(int layer, int lane, int rep, LAS unsigned char* lds, int wave) {
;     ...
;             for (;;) { WG_DRAW(0, q); if (it >= 32) break;
.LBB0_552:
	s_and_saveexec_b64 s[14:15], s[70:71]
	s_cbranch_execz .LBB0_556
	s_load_dwordx2 s[22:23], s[0:1], 0x98
	s_mov_b64 s[16:17], exec
	v_mbcnt_lo_u32_b32 v2, s16, 0
	v_mbcnt_hi_u32_b32 v2, s17, v2
	v_cmp_eq_u32_e32 vcc, 0, v2
	s_and_saveexec_b64 s[20:21], vcc
	s_cbranch_execz .LBB0_555
	s_waitcnt lgkmcnt(0)
	s_add_u32 s4, s22, s26
	s_addc_u32 s5, s23, s27
	s_lshl_b32 s11, s101, 6
	s_add_u32 s4, s4, s11
	s_addc_u32 s5, s5, 0
	s_bcnt1_i32_b64 s11, s[16:17]
	v_mov_b32_e32 v4, s11
	global_atomic_add v4, v231, v4, s[4:5] sc0

; #define LAS __attribute__((address_space(3)))
; __device__ __forceinline__ float wave_sum(float v) { v += lx<1>(v); v += lx<2>(v); v += lx<4>(v); v += lx<8>(v); v += lx<16>(v); return half_sum(v); }
; __device__ __forceinline__ size_t vtb_off(int b, int hs, int kb) { return ((size_t)(b * NHS + hs) * VTB_KB + kb) * 4096; }
; #define ARG_IN(i) ((const float*)karg64(8 * (i)))
; #define ARG_WS() ((unsigned char*)karg64(8 * 19))
; __device__ __forceinline__ void dif_coop(const bf16* PROJ, const unsigned char* VTB, bf16* O, float lam, const float* subg, float oscale, int bh, int c, LAS unsigned char* sbuf, int tid) {
;     const int wave = tid >> 6, lane = tid & 63, b = bh >> 2, hd = bh & 3, q = lane & 31, hh = lane >> 5, mp = wave >> 2, qt = 4 * c + (wave & 3), tq = 32 * qt + q; const size_t row = (size_t)b * SEQ + tq;
;     AlibiCausal f; f.setup(__builtin_amdgcn_exp2f(-2.f * (float)(hd + 1)) * LOG2E, hh); f.tq = tq; f.t0 = 32 * qt;
;     bf16x8 qf[4]; load_qfrag(PROJ + row * NINP + C_DIFQ + hd * 128 + mp * 64 + 8 * hh, qf);
;     f32x16 o[4]; zero_ot<4>(o); float m = NEG_BIG, l = 0.f;
;     const bf16* kc = PROJ + (size_t)b * SEQ * NINP + C_DIFK + hd * 128;
;     coop_pass<4, 2>(qf, kc, kc + 64, VTB + vtb_off(b, 20 + 2 * hd, 0), VTB + vtb_off(b, 21 + 2 * hd, 0), f, (4 * c + 3) >> 1, 32 * qt, mp, sbuf, tid, hh, o, m, l);
; template <int ATTM> __device__ __forceinline__ void attention_phase(int layer, int lane, int rep, LAS unsigned char* lds, int wave) {
;     ...
;             for (;;) { WG_DRAW(0, q); if (it >= 32) break;
;                 unsigned char* ws = ARG_WS(); int tid = threadIdx.x; asm volatile("" : "+v"(tid));
;                 const float* lamv = ARG_IN(A_LAM) + (size_t)layer * 4 * 64;
;                 const float lam_init = 0.8f - 0.6f * __builtin_amdgcn_exp2f(-0.3f * 1.4426950408889634f * (float)layer);
;                 const float sa = wave_sum(lamv[lane] * lamv[64 + lane]), sb = wave_sum(lamv[128 + lane] * lamv[192 + lane]);
;                 const float lam = __builtin_amdgcn_exp2f(1.4426950408889634f * sa) - __builtin_amdgcn_exp2f(1.4426950408889634f * sb) + lam_init;
;                 dif_coop(WSP(bf16, WS_PROJ), ws + WS_VTB, WSP(bf16, WS_O), lam, ARG_IN(A_SUBG) + (size_t)layer * 128, 1.f - lam_init, q, 31 - it, lds, tid); } } }
.LBB0_556:
	s_or_b64 exec, exec, s[14:15]
	v_mov_b32_e32 v2, s87
	s_waitcnt vmcnt(0) lgkmcnt(0)
	s_barrier
	ds_read_b32 v2, v2
	s_mov_b64 s[14:15], -1
	s_waitcnt lgkmcnt(0)
	s_barrier
	s_lshl_b32 s4, s101, 4
	v_add_u32_e32 v2, s4, v2
	s_lshl_b32 s4, 16, s101
	v_cmp_le_i32_e32 vcc, s4, v2
	v_readfirstlane_b32 s4, v2
	s_cbranch_vccnz .LBB0_551
	v_mov_b32_e32 v184, v0
	s_load_dwordx2 s[36:37], s[0:1], 0x98
	s_load_dwordx2 s[12:13], s[0:1], 0x58
	v_mov_b32_e32 v173, v3
	s_movk_i32 s5, 0x1800
	v_bfe_u32 v29, v184, 5, 1
	v_ashrrev_i32_e32 v31, 8, v184
	s_waitcnt lgkmcnt(0)
	s_add_u32 s12, s12, s2
	s_addc_u32 s13, s13, s3
	v_lshl_add_u64 v[20:21], s[12:13], 0, v[172:173]
	flat_load_dword v2, v[20:21]
	flat_load_dword v22, v[20:21] offset:256
	v_lshlrev_b32_e32 v33, 4, v184
	v_and_b32_e32 v34, 48, v184
	v_lshrrev_b32_e32 v35, 1, v184
	v_and_b32_e32 v30, 31, v184
	v_lshlrev_b32_e32 v32, 3, v184
	v_cmp_lt_i32_e32 vcc, s80, v184
	v_lshlrev_b32_e32 v28, 6, v31
	v_lshlrev_b32_e32 v31, 13, v31
	s_movk_i32 s20, 0x1000
	v_cndmask_b32_e64 v26, 20, 21, vcc
	v_lshl_or_b32 v31, v30, 7, v31
	v_mov_b32_e32 v27, v3
	v_bfe_u32 v186, v184, 6, 2
	v_add_lshl_u32 v26, s9, v26, 19
	v_lshrrev_b32_e32 v36, 2, v184
	v_bitop3_b32 v36, v36, v29, 3 bitop3:0x6c
	v_lshlrev_b32_e32 v173, 2, v29
	v_lshlrev_b32_e32 v40, 5, v186
	v_cmp_gt_u32_e64 s[38:39], v173, v30
	v_cmp_lt_u32_e64 s[40:41], v173, v30
	v_mov_b32_e32 v25, v3
	s_mov_b32 s25, s19
	s_mov_b32 s17, s19
	v_mov_b32_e32 v37, v29
	v_mov_b32_e32 v23, v3
	v_mov_b32_e32 v175, v174
	v_mov_b32_e32 v18, v3
	v_mov_b32_e32 v19, v3
	v_mov_b32_e32 v4, v3
	v_mov_b32_e32 v5, v3
	v_mov_b32_e32 v6, v3
	v_mov_b32_e32 v7, v3
	v_mov_b32_e32 v8, v3
	v_mov_b32_e32 v9, v3
	v_mov_b32_e32 v10, v3
	v_mov_b32_e32 v11, v3
	v_mov_b32_e32 v12, v3
	v_mov_b32_e32 v13, v3
	v_mov_b32_e32 v14, v3
	v_mov_b32_e32 v15, v3
	v_mov_b32_e32 v16, v3
	v_mov_b32_e32 v187, 0
	v_mov_b32_e32 v202, 0xf149f2ca
	v_and_b32_e32 v185, 63, v184
	s_waitcnt vmcnt(0) lgkmcnt(0)
	v_mul_f32_e32 v17, v2, v22
	ds_swizzle_b32 v24, v17 offset:swizzle(SWAP,1)
	v_mov_b32_e32 v17, v3
	s_waitcnt lgkmcnt(0)
	v_fmac_f32_e32 v24, v2, v22
	ds_swizzle_b32 v2, v24 offset:swizzle(SWAP,2)
	s_waitcnt lgkmcnt(0)
	v_add_f32_e32 v2, v24, v2
	ds_swizzle_b32 v22, v2 offset:swizzle(SWAP,4)
	v_ashrrev_i32_e32 v24, 3, v184
	v_mad_i64_i32 v[178:179], s[12:13], v24, s5, 0
	s_movk_i32 s5, 0xff0
	s_waitcnt lgkmcnt(0)
	v_add_f32_e32 v2, v2, v22
	ds_swizzle_b32 v22, v2 offset:swizzle(SWAP,8)
	s_add_u32 s12, s36, 0x8800000
	v_and_or_b32 v178, v32, 56, v178
	s_addc_u32 s13, s37, 0
	s_sub_i32 s11, 31, s4
	s_waitcnt lgkmcnt(0)
	v_add_f32_e32 v2, v2, v22
	ds_swizzle_b32 v22, v2 offset:swizzle(SWAP,16)
	s_lshl_b32 s16, s11, 2
	s_lshl_b32 s24, s8, 1
	s_waitcnt lgkmcnt(0)
	v_add_f32_e32 v188, v2, v22
	v_mov_b32_e32 v189, v188
	flat_load_dword v38, v[20:21] offset:512
	flat_load_dword v39, v[20:21] offset:768
	v_lshlrev_b32_e32 v2, 7, v24
	v_xor_b32_e32 v20, v33, v184
	v_bitop3_b32 v21, v33, v34, s5 bitop3:0x6c
	v_bitop3_b32 v34, v35, v29, 7 bitop3:0x6c
	v_and_b32_e32 v24, 0xff0, v33
	v_and_or_b32 v2, v20, s85, v2
	v_and_or_b32 v32, v33, s20, v21
	v_lshlrev_b32_e32 v33, 4, v34
	v_add_u32_e32 v190, 0, v2
	v_bitop3_b32 v2, v33, 32, v31 bitop3:0x36
	v_lshl_add_u64 v[20:21], s[36:37], 0, v[26:27]
	v_or_b32_e32 v26, v33, v31
	v_add_u32_e32 v193, 0, v2
	v_or_b32_e32 v2, s16, v186
	v_add_u32_e32 v192, 0, v26
	v_lshlrev_b32_e32 v197, 5, v2
	v_lshlrev_b32_e32 v35, 6, v30
	v_lshlrev_b32_e32 v34, 4, v36
	v_or_b32_e32 v36, v40, v30
	v_or_b32_e32 v42, v197, v30
	v_add_u32_e32 v191, 0, v32
	v_bitop3_b32 v32, v33, 64, v31 bitop3:0x36
	v_bitop3_b32 v31, v33, s81, v31 bitop3:0x36
	v_add_u32_e32 v195, 0, v31
	v_or_b32_e32 v27, v34, v35
	v_bitop3_b32 v41, v34, 32, v35 bitop3:0x36
	v_lshl_add_u64 v[20:21], v[20:21], 0, v[24:25]
	s_add_u32 s5, s12, s10
	v_lshl_add_u64 v[180:181], v[20:21], 0, s[96:97]
	v_mov_b64_e32 v[20:21], s[12:13]
	s_addc_u32 s12, s13, 0
	s_add_u32 s5, s5, s24
	v_add_u32_e32 v2, s7, v42
	s_addc_u32 s15, s12, 0
	v_mad_u64_u32 v[20:21], s[12:13], v2, s83, v[20:21]
	s_add_u32 s14, s5, 0x2600
	v_lshlrev_b32_e32 v22, 4, v29
	v_ashrrev_i32_e32 v29, 31, v28
	v_lshl_add_u64 v[20:21], v[20:21], 0, s[24:25]
	s_addc_u32 s15, s15, 0
	s_lshr_b32 s5, s16, 1
	s_lshl_b64 s[12:13], s[16:17], 12
	s_lshl_b32 s16, s11, 7
	v_add_u32_e32 v196, 0, v27
	v_lshl_add_u64 v[24:25], v[28:29], 1, v[20:21]
	s_or_b32 s11, s5, 1
	v_lshl_add_u64 v[20:21], v[180:181], 0, s[12:13]
	v_lshl_add_u64 v[22:23], v[24:25], 0, v[22:23]
	v_add_co_u32_e32 v24, vcc, s20, v20
	s_lshl_b32 s18, s11, 1
	s_nop 0
	v_addc_co_u32_e32 v25, vcc, 0, v21, vcc
	v_add_u32_e32 v194, 0, v32
	v_or_b32_e32 v43, v197, v173
	s_lshl_b32 s5, s5, 6
	v_or_b32_e32 v44, 2, v43
	v_or_b32_e32 v45, 3, v43
	v_or_b32_e32 v46, 8, v43
	v_or_b32_e32 v47, 9, v43
	v_or_b32_e32 v48, 10, v43
	v_or_b32_e32 v49, 11, v43
	v_or_b32_e32 v50, 16, v43
	v_or_b32_e32 v51, 17, v43
	v_or_b32_e32 v52, 18, v43
	v_or_b32_e32 v53, 19, v43
	v_or_b32_e32 v54, 24, v43
	v_or_b32_e32 v55, 25, v43
	v_or_b32_e32 v56, 26, v43
	v_cmp_gt_u32_e64 s[42:43], v44, v42
	v_cmp_gt_u32_e64 s[44:45], v45, v42
	v_cmp_gt_u32_e64 s[46:47], v46, v42
	v_cmp_gt_u32_e64 s[48:49], v47, v42
	v_cmp_gt_u32_e64 s[50:51], v48, v42
	v_cmp_gt_u32_e64 s[52:53], v49, v42
	v_cmp_gt_u32_e64 s[54:55], v50, v42
	v_cmp_gt_u32_e64 s[56:57], v51, v42
	v_cmp_gt_u32_e64 s[58:59], v52, v42
	s_waitcnt vmcnt(0) lgkmcnt(0)
; #define LAS __attribute__((address_space(3)))
; __device__ __forceinline__ size_t vtb_off(int b, int hs, int kb) { return ((size_t)(b * NHS + hs) * VTB_KB + kb) * 4096; }
; __device__ __forceinline__ int swz_v(int off) { const int d = (off >> 6) & 31; return (off & ~0x30) | ((((off >> 4) & 3) ^ ((d >> 2) & 3)) << 4); }
; template <int NDT, int NMAP, class F> ...
;     typedef CoopGeom<NDT, NMAP> Gm;
;     const int lane = tid & 63;
;     const int skey = tid >> 3, sch = tid & 7;
;     const size_t ksoff = (size_t)skey * NINP + sch * 8;
;     const int kdst = skey * 128 + ((sch ^ ((skey >> 1) & 7)) << 4);
;     const int w8 = tid * 16;
;     const unsigned char* vsrc = (NDT == 4 ? ((w8 >= 4096 ? vtb1 : vtb0) + (w8 & 4095)) : (vtb0 + (size_t)(w8 >> 12) * 4096 + (w8 & 4095)));
;     const int vdst = Gm::KB + (NDT == 4 ? ((w8 & 4096) + swz_v(w8 & 4095)) : ((w8 >> 12) * Gm::VS + swz_v(w8 & 4095)));
;     const int fk = mapsel * 8192 + (lane & 31) * 128 + ((hh ^ (((lane & 31) >> 1) & 7)) << 4);
;     const int fv = Gm::KB + (lane & 31) * 64 + ((hh ^ (((lane & 31) >> 2) & 3)) << 4);
;     v4u kr0[2], kr1[2], vr0[2], vr1[2];
;     ...
;     LAS unsigned char* b0 = sbuf; LAS unsigned char* b1 = sbuf + Gm::TB;
;     CP_LOAD(0, step_last); if (step_last >= 1) CP_LOAD(1, step_last - 1);
;     const int t0u = __builtin_amdgcn_readfirstlane(t0_mine);
;     f.fetch2(t0u >> 6);
;     CP_PARK(0, b0);
;     CP_BAR();
; __device__ __forceinline__ void dif_coop(const bf16* PROJ, const unsigned char* VTB, bf16* O, float lam, const float* subg, float oscale, int bh, int c, LAS unsigned char* sbuf, int tid) {
;     const int wave = tid >> 6, lane = tid & 63, b = bh >> 2, hd = bh & 3, q = lane & 31, hh = lane >> 5, mp = wave >> 2, qt = 4 * c + (wave & 3), tq = 32 * qt + q; const size_t row = (size_t)b * SEQ + tq;
;     AlibiCausal f; f.setup(__builtin_amdgcn_exp2f(-2.f * (float)(hd + 1)) * LOG2E, hh); f.tq = tq; f.t0 = 32 * qt;
;     bf16x8 qf[4]; load_qfrag(PROJ + row * NINP + C_DIFQ + hd * 128 + mp * 64 + 8 * hh, qf);
;     f32x16 o[4]; zero_ot<4>(o); float m = NEG_BIG, l = 0.f;
;     const bf16* kc = PROJ + (size_t)b * SEQ * NINP + C_DIFK + hd * 128;
;     coop_pass<4, 2>(qf, kc, kc + 64, VTB + vtb_off(b, 20 + 2 * hd, 0), VTB + vtb_off(b, 21 + 2 * hd, 0), f, (4 * c + 3) >> 1, 32 * qt, mp, sbuf, tid, hh, o, m, l);
	v_mul_f32_e32 v26, v38, v39
	ds_swizzle_b32 v30, v26 offset:swizzle(SWAP,1)
	v_mad_u64_u32 v[26:27], s[12:13], s16, v237, v[178:179]
	s_lshl_b32 s12, s11, 6
	s_mov_b64 s[16:17], 0x2200
	s_waitcnt lgkmcnt(0)
	v_fmac_f32_e32 v30, v38, v39
	ds_swizzle_b32 v31, v30 offset:swizzle(SWAP,2)
	v_lshl_add_u64 v[28:29], v[22:23], 0, s[16:17]
	v_add_co_u32_e32 v22, vcc, s35, v22
	v_lshl_add_u64 v[26:27], v[26:27], 1, s[14:15]
	s_waitcnt lgkmcnt(0)
	v_add_f32_e32 v30, v30, v31
	ds_swizzle_b32 v31, v30 offset:swizzle(SWAP,4)
	v_addc_co_u32_e32 v23, vcc, 0, v23, vcc
	v_cmp_gt_u32_e64 s[60:61], v53, v42
	v_cmp_gt_u32_e64 s[62:63], v54, v42
	s_waitcnt lgkmcnt(0)
	v_add_f32_e32 v34, v30, v31
	ds_swizzle_b32 v35, v34 offset:swizzle(SWAP,8)
	v_mad_u64_u32 v[30:31], s[12:13], s12, v237, v[178:179]
	s_lshl_b64 s[12:13], s[18:19], 12
	s_nop 0
	v_lshl_add_u64 v[32:33], v[180:181], 0, s[12:13]
	s_waitcnt lgkmcnt(0)
	v_add_f32_e32 v38, v34, v35
	ds_swizzle_b32 v39, v38 offset:swizzle(SWAP,16)
	v_lshl_add_u64 v[30:31], v[30:31], 1, s[14:15]
	v_add_co_u32_e32 v34, vcc, s20, v32
	s_lshl_b32 s12, s4, 2
	s_waitcnt lgkmcnt(0)
	v_add_f32_e32 v198, v38, v39
	v_mov_b32_e32 v199, v198
	v_addc_co_u32_e32 v35, vcc, 0, v33, vcc
	s_load_dwordx2 s[16:17], s[0:1], 0x60
	global_load_dwordx4 v[116:119], v[30:31], off
	global_load_dwordx4 v[120:123], v[30:31], off offset:128
	global_load_dwordx4 v[124:127], v[32:33], off
	global_load_dwordx4 v[128:131], v[34:35], off
	global_load_dwordx4 v[100:103], v[28:29], off offset:32
	global_load_dwordx4 v[104:107], v[28:29], off offset:64
	global_load_dwordx4 v[108:111], v[22:23], off offset:512
	global_load_dwordx4 v[112:115], v[28:29], off offset:96
	global_load_dwordx4 v[144:147], v[24:25], off
	global_load_dwordx4 v[140:143], v[20:21], off
	global_load_dwordx4 v[132:135], v[26:27], off offset:128
	global_load_dwordx4 v[136:139], v[26:27], off
	v_or_b32_e32 v20, 27, v43
	v_cmp_gt_u32_e64 s[68:69], v20, v42
	s_lshl_b32 s4, s4, 7
	v_subrev_u32_e32 v20, s5, v36
	v_subrev_u32_e32 v20, s4, v20
	v_add_u32_e32 v201, 0xf20, v20
	v_lshlrev_b32_e32 v20, 2, v37
	v_or_b32_e32 v21, 1, v20
	v_or_b32_e32 v22, 3, v20
	v_or_b32_e32 v24, 2, v20
	v_add_u32_e32 v26, 8, v20
	v_add_u32_e32 v25, 9, v20
	v_add_u32_e32 v28, 10, v20
	v_add_u32_e32 v27, 11, v20
	v_add_u32_e32 v30, 16, v20
	v_add_u32_e32 v29, 17, v20
	v_add_u32_e32 v36, 18, v20
	v_add_u32_e32 v31, 19, v20
	v_add_u32_e32 v32, 24, v20
	v_add_u32_e32 v33, 25, v20
	v_add_u32_e32 v34, 26, v20
	v_add_u32_e32 v35, 27, v20
	v_cvt_f32_i32_e32 v20, v20
	v_cvt_f32_i32_e32 v23, v22
	v_cvt_f32_i32_e32 v22, v24
	v_cvt_f32_i32_e32 v21, v21
	v_cvt_f32_i32_e32 v25, v25
	v_cvt_f32_i32_e32 v24, v26
	v_cvt_f32_i32_e32 v27, v27
	v_cvt_f32_i32_e32 v26, v28
	v_cvt_f32_i32_e32 v29, v29
	v_cvt_f32_i32_e32 v28, v30
	v_cvt_f32_i32_e32 v31, v31
	v_cvt_f32_i32_e32 v33, v33
	v_cvt_f32_i32_e32 v35, v35
	v_cvt_f32_i32_e32 v34, v34
	v_cvt_f32_i32_e32 v32, v32
	v_cvt_f32_i32_e32 v30, v36
	v_cmp_gt_u32_e64 s[64:65], v55, v42
	v_cmp_gt_u32_e64 s[66:67], v56, v42
	v_sub_u32_e32 v200, s4, v40
	v_pk_mul_f32 v[70:71], v[174:175], v[22:23]
	v_pk_mul_f32 v[82:83], v[174:175], v[34:35]
	v_pk_mul_f32 v[80:81], v[174:175], v[32:33]
	v_pk_mul_f32 v[78:79], v[174:175], v[30:31]
	v_pk_mul_f32 v[76:77], v[174:175], v[28:29]
	v_pk_mul_f32 v[74:75], v[174:175], v[26:27]
	v_pk_mul_f32 v[72:73], v[174:175], v[24:25]
	v_pk_mul_f32 v[68:69], v[176:177], v[20:21]
	v_add_u32_e32 v175, 0, v41
	v_mov_b64_e32 v[34:35], v[18:19]
	v_mov_b64_e32 v[50:51], v[18:19]
	v_mov_b64_e32 v[66:67], v[18:19]
	s_sub_i32 s22, 0x78, s12
	s_add_i32 s25, s5, 0xffffff80
	v_permlane32_swap_b32_e32 v188, v189
	v_permlane32_swap_b32_e32 v198, v199
	v_mov_b64_e32 v[32:33], v[16:17]
	v_mov_b64_e32 v[30:31], v[14:15]
	v_mov_b64_e32 v[28:29], v[12:13]
	v_mov_b64_e32 v[26:27], v[10:11]
	s_waitcnt vmcnt(11)
	ds_write_b128 v190, v[116:119]
	s_waitcnt vmcnt(10)
	ds_write_b128 v190, v[120:123] offset:8192
	s_waitcnt vmcnt(9)
	ds_write_b128 v191, v[124:127] offset:16384
	s_waitcnt vmcnt(8)
	ds_write_b128 v191, v[128:131] offset:24576
	s_waitcnt lgkmcnt(0)
	s_barrier
	v_mov_b64_e32 v[24:25], v[8:9]
	v_mov_b64_e32 v[22:23], v[6:7]
	v_mov_b64_e32 v[20:21], v[4:5]
	v_mov_b64_e32 v[48:49], v[16:17]
	v_mov_b64_e32 v[46:47], v[14:15]
	v_mov_b64_e32 v[44:45], v[12:13]
	v_mov_b64_e32 v[42:43], v[10:11]
	v_mov_b64_e32 v[40:41], v[8:9]
	v_mov_b64_e32 v[38:39], v[6:7]
	v_mov_b64_e32 v[36:37], v[4:5]
	v_mov_b64_e32 v[64:65], v[16:17]
	v_mov_b64_e32 v[62:63], v[14:15]
	v_mov_b64_e32 v[60:61], v[12:13]
	v_mov_b64_e32 v[58:59], v[10:11]
	v_mov_b64_e32 v[56:57], v[8:9]
	v_mov_b64_e32 v[54:55], v[6:7]
	v_mov_b64_e32 v[52:53], v[4:5]
	s_branch .LBB0_559

; #define ARG_WS() ((unsigned char*)karg64(8 * 19))
; #define WG_DRAW(cls, q) LAS int* slot = (LAS int*)(lds + MISC_OFF + 64); \
;         if (threadIdx.x == 0) *slot = (int)__hip_atomic_fetch_add(XQ_HEAD(cls, q), 1u, RLX_AGENT); \
;         __syncthreads(); const int it = *slot; __syncthreads();
; template <int ATTM> __device__ __forceinline__ void attention_phase(int layer, int lane, int rep, LAS unsigned char* lds, int wave) {
;     ...
;             for (;;) { WG_DRAW(1, q); if (it >= (two ? 32 : 16)) break;
;                 unsigned char* ws = ARG_WS(); int tid = threadIdx.x; asm volatile("" : "+v"(tid));
;                 const int bh = two ? ((it & 1) ? q + 8 : q) : q, c = 15 - (two ? (it >> 1) : it);
.LBB0_619:
	s_and_saveexec_b64 s[16:17], s[70:71]
	s_cbranch_execz .LBB0_623
	s_load_dwordx2 s[24:25], s[0:1], 0x98
	s_mov_b64 s[20:21], exec
	v_mbcnt_lo_u32_b32 v1, s20, 0
	v_mbcnt_hi_u32_b32 v1, s21, v1
	v_cmp_eq_u32_e32 vcc, 0, v1
	s_and_saveexec_b64 s[22:23], vcc
	s_cbranch_execz .LBB0_622
	s_waitcnt lgkmcnt(0)
	s_add_u32 s4, s24, s14
	s_addc_u32 s5, s25, s15
	s_lshl_b32 s11, s101, 6
	s_add_u32 s4, s4, s11
	s_addc_u32 s5, s5, 0
	s_bcnt1_i32_b64 s11, s[20:21]
	v_mov_b32_e32 v2, s11
	global_atomic_add v2, v231, v2, s[4:5] sc0

; #define LAS __attribute__((address_space(3)))
; __device__ __forceinline__ size_t vtb_off(int b, int hs, int kb) { return ((size_t)(b * NHS + hs) * VTB_KB + kb) * 4096; }
; #define ARG_WS() ((unsigned char*)karg64(8 * 19))
; #define WG_DRAW(cls, q) LAS int* slot = (LAS int*)(lds + MISC_OFF + 64); \
;         if (threadIdx.x == 0) *slot = (int)__hip_atomic_fetch_add(XQ_HEAD(cls, q), 1u, RLX_AGENT); \
;         __syncthreads(); const int it = *slot; __syncthreads();
; __device__ __forceinline__ void fox_coop(const bf16* PROJ, const float* CUM, const unsigned char* VTB, bf16* O, int bh, int c, LAS unsigned char* sbuf, int tid) {
;     const int wave = tid >> 6, lane = tid & 63, b = bh / 7, hd = bh % 7, q = lane & 31, hh = lane >> 5, qt = 8 * c + wave, tq = 32 * qt + q; const size_t row = (size_t)b * SEQ + tq;
;     bf16x8 qf[4]; load_qfrag(PROJ + row * NINP + C_FOXQ + hd * 64 + 8 * hh, qf);
;     ...
;     f32x16 o[2]; zero_ot<2>(o); float m = NEG_BIG, l = 0.f;
;     const bf16* kc = PROJ + (size_t)b * SEQ * NINP + C_FOXK + hd * 64;
;     coop_pass<2, 1>(qf, kc, kc, VTB + vtb_off(b, hd, 0), VTB, f, 4 * c + 3, 32 * qt, 0, sbuf, tid, hh, o, m, l);
; template <int ATTM> __device__ __forceinline__ void attention_phase(int layer, int lane, int rep, LAS unsigned char* lds, int wave) {
;     ...
;             for (;;) { WG_DRAW(1, q); if (it >= (two ? 32 : 16)) break;
;                 unsigned char* ws = ARG_WS(); int tid = threadIdx.x; asm volatile("" : "+v"(tid));
;                 const int bh = two ? ((it & 1) ? q + 8 : q) : q, c = 15 - (two ? (it >> 1) : it);
;                 fox_coop(WSP(bf16, WS_PROJ), WSP(float, WS_CUM), ws + WS_VTB, WSP(bf16, WS_O), bh, c, lds, tid); } } }
.LBB0_623:
	s_or_b64 exec, exec, s[16:17]
	v_mov_b32_e32 v1, s87
	s_waitcnt lgkmcnt(0)
	s_barrier
	ds_read_b32 v1, v1
	s_mov_b64 s[16:17], -1
	s_waitcnt lgkmcnt(0)
	s_barrier
	s_lshr_b32 s4, s9, 1
	s_mul_i32 s4, s4, s101
	v_add_u32_e32 v1, s4, v1
	s_lshr_b32 s4, s9, 1
	s_lshl_b32 s4, s4, s101
	v_cmp_le_i32_e32 vcc, s4, v1
	v_readfirstlane_b32 s4, v1
	s_cbranch_vccnz .LBB0_618
	s_load_dwordx2 s[26:27], s[0:1], 0x98
	s_lshl_b32 s5, s4, 3
	s_and_b32 s5, s5, 8
	s_and_b64 s[12:13], s[2:3], exec
	s_cselect_b32 s5, s5, 0
	s_ashr_i32 s4, s4, s10
	s_or_b32 s5, s5, s8
	s_sub_i32 s24, 15, s4
	v_mov_b32_e32 v8, v0
	s_waitcnt lgkmcnt(0)
	s_add_u32 s12, s26, 0x8800000
	v_sub_co_u32_e64 v1, s[16:17], s5, 7
	s_addc_u32 s13, s27, 0
	v_readfirstlane_b32 s11, v1
	v_ashrrev_i32_e32 v1, 1, v8
	s_cmp_gt_u32 s5, 6
	v_and_b32_e32 v1, 0xffffffe0, v1
	s_cselect_b64 s[20:21], -1, 0
	s_and_b64 s[16:17], s[16:17], exec
	v_and_b32_e32 v10, 31, v8
	v_lshl_add_u32 v1, s24, 8, v1
	s_cselect_b32 s11, s5, s11
	v_or_b32_e32 v220, v1, v10
	s_and_b64 s[16:17], s[20:21], exec
	s_cselect_b32 s18, 0x1000, 0
	v_ashrrev_i32_e32 v221, 31, v220
	v_lshl_add_u64 v[218:219], s[18:19], 0, v[220:221]
	v_mov_b64_e32 v[4:5], s[12:13]
	s_lshl_b32 s22, s11, 7
	s_lshl_b32 s5, s5, 14
	v_mad_u64_u32 v[4:5], s[16:17], v218, s83, v[4:5]
	s_add_u32 s5, s26, s5
	s_addc_u32 s17, s27, 0
	s_add_u32 s16, s5, 0x200000
	s_addc_u32 s17, s17, 0
	s_mul_i32 s5, s18, 0x3000
	s_add_u32 s5, s12, s5
	s_addc_u32 s13, s13, 0
	s_add_u32 s12, s5, s22
	s_addc_u32 s13, s13, 0
	s_and_b64 s[20:21], s[20:21], exec
	v_bfe_u32 v9, v8, 5, 1
	v_mad_i32_i24 v5, v219, s83, v5
	s_mov_b32 s23, s19
	s_cselect_b32 s5, 28, 0
	v_lshl_add_u64 v[4:5], v[4:5], 0, s[22:23]
	v_lshlrev_b32_e32 v2, 4, v9
	s_add_i32 s18, s5, s11
	v_lshl_add_u64 v[4:5], v[4:5], 0, v[2:3]
	s_lshl_b64 s[20:21], s[18:19], 19
	v_ashrrev_i32_e32 v6, 8, v8
	global_load_dwordx4 v[162:165], v[4:5], off
	global_load_dwordx4 v[166:169], v[4:5], off offset:32
	global_load_dwordx4 v[170:173], v[4:5], off offset:64
	global_load_dwordx4 v[174:177], v[4:5], off offset:96
	v_lshl_add_u64 v[4:5], v[220:221], 2, s[16:17]
	s_add_u32 s20, s26, s20
	v_ashrrev_i32_e32 v7, 31, v6
	flat_load_dword v11, v[4:5]
	s_addc_u32 s21, s27, s21
	v_lshlrev_b32_e32 v13, 4, v8
	v_lshlrev_b64 v[4:5], 12, v[6:7]
	v_lshl_add_u64 v[14:15], s[20:21], 0, v[4:5]
	v_and_b32_e32 v4, 0xff0, v13
	v_mov_b32_e32 v5, v3
	s_lshl_b32 s5, s24, 2
	v_lshl_add_u64 v[14:15], v[14:15], 0, v[4:5]
	s_or_b32 s18, s5, 3
	v_ashrrev_i32_e32 v12, 3, v8
	v_lshl_add_u64 v[222:223], v[14:15], 0, s[96:97]
	v_mov_b64_e32 v[14:15], s[12:13]
	s_lshl_b32 s20, s18, 1
	v_mad_i64_i32 v[14:15], s[12:13], v12, s83, v[14:15]
	v_and_b32_e32 v16, 0x70, v13
	v_mov_b32_e32 v17, v3
	s_lshl_b32 s22, s18, 6
	s_ashr_i32 s21, s20, 31
	v_lshl_add_u64 v[224:225], v[14:15], 0, v[16:17]
	s_lshl_b64 s[20:21], s[20:21], 12
	v_mad_i64_i32 v[14:15], s[12:13], s22, v238, v[224:225]
	v_lshl_add_u64 v[16:17], v[222:223], 0, s[20:21]
	global_load_dwordx4 v[178:181], v[14:15], off offset:896
	global_load_dwordx4 v[182:185], v[16:17], off
	s_cmp_lt_i32 s4, 16
	s_cselect_b64 s[20:21], -1, 0
	s_cmp_gt_i32 s4, 15
	s_cbranch_scc1 .LBB0_626
	s_or_b32 s5, s5, 2
	s_lshl_b32 s22, s5, 6
	s_lshl_b32 s18, s5, 1
	s_lshl_b64 s[12:13], s[18:19], 12
	v_mad_u64_u32 v[14:15], s[22:23], s22, v238, v[224:225]
	v_lshl_add_u64 v[16:17], v[222:223], 0, s[12:13]
	global_load_dwordx4 v[186:189], v[14:15], off offset:896
	global_load_dwordx4 v[190:193], v[16:17], off

; #define ARG_WS() ((unsigned char*)karg64(8 * 19))
; #define WG_DRAW(cls, q) LAS int* slot = (LAS int*)(lds + MISC_OFF + 64); \
;         if (threadIdx.x == 0) *slot = (int)__hip_atomic_fetch_add(XQ_HEAD(cls, q), 1u, RLX_AGENT); \
;         __syncthreads(); const int it = *slot; __syncthreads();
; template <int ATTM> __device__ __forceinline__ void attention_phase(int layer, int lane, int rep, LAS unsigned char* lds, int wave) {
;     ...
;             for (;;) { WG_DRAW(2, q); if (it >= 32) break; unsigned char* ws = ARG_WS();
;                 nsa_quad_item(WSP(bf16, WS_PROJ), WSP(bf16, WS_KC), ws + WS_VCB, ws + WS_VTB, WSP(unsigned long long, WS_SEL), WSP(bf16, WS_O), lds, q >> 1, 2 * (31 - it) + (q & 1), wave); } } }
.LBB0_674:
	s_and_saveexec_b64 s[14:15], s[70:71]
	s_cbranch_execz .LBB0_678
	s_load_dwordx2 s[22:23], s[0:1], 0x98
	s_mov_b64 s[16:17], exec
	v_mbcnt_lo_u32_b32 v2, s16, 0
	v_mbcnt_hi_u32_b32 v2, s17, v2
	v_cmp_eq_u32_e32 vcc, 0, v2
	s_and_saveexec_b64 s[20:21], vcc
	s_cbranch_execz .LBB0_677
	s_waitcnt lgkmcnt(0)
	s_add_u32 s4, s22, s2
	s_addc_u32 s5, s23, s3
	s_lshl_b32 s6, s101, 6
	s_add_u32 s4, s4, s6
	s_addc_u32 s5, s5, 0
	s_bcnt1_i32_b64 s6, s[16:17]
	v_mov_b32_e32 v4, s6
	global_atomic_add v4, v231, v4, s[4:5] sc0

; #define LAS __attribute__((address_space(3)))
; template <int K> __device__ __forceinline__ int lx_i(int v) { static_assert(K >= 1 && K < 32, ""); return __builtin_amdgcn_ds_swizzle(v, (K << 10) | 0x1f); }
; __device__ __forceinline__ unsigned long long tile_union(unsigned long long mask) {
;     unsigned ulo = (unsigned)mask, uhi = (unsigned)(mask >> 32);
;     ulo |= (unsigned)lx_i<1>((int)ulo); uhi |= (unsigned)lx_i<1>((int)uhi); ulo |= (unsigned)lx_i<2>((int)ulo); uhi |= (unsigned)lx_i<2>((int)uhi); ulo |= (unsigned)lx_i<4>((int)ulo); uhi |= (unsigned)lx_i<4>((int)uhi);
;     ulo |= (unsigned)lx_i<8>((int)ulo); uhi |= (unsigned)lx_i<8>((int)uhi); ulo |= (unsigned)lx_i<16>((int)ulo); uhi |= (unsigned)lx_i<16>((int)uhi);
;     return (unsigned long long)(unsigned)__builtin_amdgcn_readfirstlane((int)ulo) | ((unsigned long long)(unsigned)__builtin_amdgcn_readfirstlane((int)uhi) << 32); }
; __device__ __forceinline__ void nsa_quad_item(const bf16* PROJ, const bf16* KC, const unsigned char* VCB, const unsigned char* VTB, const unsigned long long* SEL, bf16* O, LAS unsigned char* lds, int bg, int jp, int wave) {
;     const int lane = fresh_lane();
;     const int b = bg >> 1, g = bg & 1, wi = wave & 3, qd = wave >> 2, hd = 4 * g + wi, qt = 2 * jp + qd, qto = 2 * jp + (qd ^ 1), q = lane & 31, hh = lane >> 5, t0 = qt * 32, tq = t0 + q, tmax = t0 + 31;
;     LAS unsigned char* ring = lds + qd * 65536;
;     ...
;     const float slope2 = __builtin_amdgcn_exp2f(-(float)(hd + 1)) * LOG2E;
;     bf16x8 qf[4]; load_qfrag(PROJ + NSA_ROW() * NINP + C_NSAQ + hd * 64 + 8 * hh, qf);
;     f32x16 o[2]; unsigned res[16];
;     {
;         const unsigned long long mask = SEL[(size_t)(b * 2 + g) * SEQ + tq], masko = SEL[(size_t)(b * 2 + g) * SEQ + 32 * qto + q];
;         const unsigned long long um = tile_union(mask), umo = tile_union(masko);
;         const int n_own = slc_tiles(um, t0), n_oth = slc_tiles(umo, 32 * qto);
;         SlcBias f; f.setup(slope2, hh); f.tq = tq;
;         QuadStream st; st.setup(PROJ + (size_t)b * SEQ * NINP + C_SLCK + g * 64, (size_t)NINP * 2, VTB + vtb_off(b, 7 + g, 0), lane, wi);
;         zero_ot<2>(o); float m = NEG_BIG, l = 0.f;
;         SlcIt it; it.um = um; it.pend = -1; it.tmax = tmax; SlcPre pre{f, mask, t0};
;         quad_stream(qf, st, ring, f, it, it, pre, n_own, n_own > n_oth ? n_own : n_oth, hh, o, m, l);
.LBB0_678:
	s_or_b64 exec, exec, s[14:15]
	v_mov_b32_e32 v2, s87
	s_waitcnt lgkmcnt(0)
	s_barrier
	ds_read_b32 v2, v2
	s_mov_b64 s[14:15], -1
	s_waitcnt lgkmcnt(0)
	s_barrier
	s_lshl_b32 s4, s101, 4
	v_add_u32_e32 v2, s4, v2
	s_lshl_b32 s4, 16, s101
	v_cmp_le_i32_e32 vcc, s4, v2
	v_readfirstlane_b32 s4, v2
	s_cbranch_vccnz .LBB0_673
	s_load_dwordx2 s[26:27], s[0:1], 0x98
	s_waitcnt vmcnt(0)
	v_mov_b32_e32 v118, v239
	v_mov_b32_e32 v4, v239
	s_waitcnt lgkmcnt(0)
	s_add_u32 s14, s26, 0x8800000
	s_addc_u32 s15, s27, 0
	s_lshl_b32 s97, s4, 2
	s_sub_i32 s4, s64, s97
	s_add_i32 s10, s4, 0x7c
	s_add_i32 s8, s10, s48
	s_lshl_b32 s9, s8, 5
	s_add_i32 s10, s10, s49
	s_or_b32 s4, s9, 31
	s_ashr_i32 s5, s9, 31
	s_add_u32 s6, s9, s65
	s_addc_u32 s7, s5, 0
	v_and_or_b32 v6, v4, 31, s6
	v_mov_b64_e32 v[4:5], s[14:15]
	s_lshl_b32 s44, s66, 1
	v_ashrrev_i32_e32 v102, 5, v118
	v_mad_u64_u32 v[4:5], s[16:17], v6, s83, v[4:5]
	s_add_u32 s5, s26, s67
	v_and_b32_e32 v2, 31, v118
	v_mad_i32_i24 v5, s7, v238, v5
	s_mov_b32 s45, s19
	v_lshlrev_b32_e32 v6, 3, v102
	s_addc_u32 s11, s27, 0
	v_or_b32_e32 v116, s9, v2
	v_lshl_add_u64 v[4:5], v[4:5], 0, s[44:45]
	v_ashrrev_i32_e32 v7, 31, v6
	s_add_u32 s16, s5, 0x400000
	v_lshl_add_u64 v[4:5], v[6:7], 1, v[4:5]
	v_ashrrev_i32_e32 v117, 31, v116
	s_addc_u32 s17, s11, 0
	global_load_dwordx4 v[132:135], v[4:5], off offset:2688
	global_load_dwordx4 v[136:139], v[4:5], off offset:2720
	global_load_dwordx4 v[140:143], v[4:5], off offset:2752
	global_load_dwordx4 v[144:147], v[4:5], off offset:2784
	v_lshl_add_u64 v[4:5], v[116:117], 3, s[16:17]
	flat_load_dwordx2 v[68:69], v[4:5]
	s_lshl_b32 s22, s10, 5
	s_ashr_i32 s23, s22, 31
	s_lshl_b64 s[20:21], s[22:23], 3
	s_add_u32 s16, s16, s20
	s_addc_u32 s17, s17, s21
	v_lshlrev_b32_e32 v2, 3, v2
	v_lshl_add_u64 v[4:5], s[16:17], 0, v[2:3]
	flat_load_dwordx2 v[4:5], v[4:5]
	s_mov_b32 s18, 0
	s_mov_b32 s12, -1
	s_mov_b64 s[24:25], 0
	s_mov_b32 s13, -1
	s_waitcnt vmcnt(0) lgkmcnt(0)
	ds_swizzle_b32 v2, v68 offset:swizzle(SWAP,1)
	ds_swizzle_b32 v6, v69 offset:swizzle(SWAP,1)
	s_waitcnt lgkmcnt(1)
	v_or_b32_e32 v2, v2, v68
	ds_swizzle_b32 v7, v2 offset:swizzle(SWAP,2)
	s_waitcnt lgkmcnt(1)
	v_or_b32_e32 v6, v6, v69
	s_waitcnt lgkmcnt(0)
	v_or_b32_e32 v2, v7, v2
	ds_swizzle_b32 v7, v6 offset:swizzle(SWAP,2)
	s_waitcnt lgkmcnt(0)
	v_or_b32_e32 v6, v7, v6
	ds_swizzle_b32 v7, v2 offset:swizzle(SWAP,4)
	s_waitcnt lgkmcnt(0)
	v_or_b32_e32 v2, v7, v2
	ds_swizzle_b32 v7, v6 offset:swizzle(SWAP,4)
	s_waitcnt lgkmcnt(0)
	v_or_b32_e32 v6, v7, v6
	ds_swizzle_b32 v7, v2 offset:swizzle(SWAP,8)
	s_waitcnt lgkmcnt(0)
	v_or_b32_e32 v2, v7, v2
	ds_swizzle_b32 v7, v6 offset:swizzle(SWAP,8)
	s_waitcnt lgkmcnt(0)
	v_or_b32_e32 v6, v7, v6
	ds_swizzle_b32 v7, v2 offset:swizzle(SWAP,16)
	s_waitcnt lgkmcnt(0)
	v_or_b32_e32 v2, v7, v2
	s_nop 0
	v_readfirstlane_b32 s16, v2
	ds_swizzle_b32 v2, v4 offset:swizzle(SWAP,1)
	ds_swizzle_b32 v7, v6 offset:swizzle(SWAP,16)
	s_waitcnt lgkmcnt(1)
	v_or_b32_e32 v2, v2, v4
	ds_swizzle_b32 v4, v5 offset:swizzle(SWAP,1)
	s_waitcnt lgkmcnt(1)
	v_or_b32_e32 v6, v7, v6
	s_waitcnt lgkmcnt(0)
	v_or_b32_e32 v4, v4, v5
	ds_swizzle_b32 v5, v2 offset:swizzle(SWAP,2)
	v_readfirstlane_b32 s17, v6
	s_cmp_eq_u64 s[16:17], 0
	s_cselect_b64 s[36:37], -1, 0
	s_cmp_lg_u64 s[16:17], 0
	s_waitcnt lgkmcnt(0)
	v_or_b32_e32 v2, v5, v2
	ds_swizzle_b32 v5, v4 offset:swizzle(SWAP,2)
	s_waitcnt lgkmcnt(0)
	v_or_b32_e32 v4, v5, v4
	ds_swizzle_b32 v5, v2 offset:swizzle(SWAP,4)
	s_waitcnt lgkmcnt(0)
	v_or_b32_e32 v2, v5, v2
	ds_swizzle_b32 v5, v4 offset:swizzle(SWAP,4)
	s_waitcnt lgkmcnt(0)
	v_or_b32_e32 v4, v5, v4
	ds_swizzle_b32 v5, v2 offset:swizzle(SWAP,8)
	s_waitcnt lgkmcnt(0)
	v_or_b32_e32 v2, v5, v2
	ds_swizzle_b32 v5, v4 offset:swizzle(SWAP,8)
	s_waitcnt lgkmcnt(0)
	v_or_b32_e32 v4, v5, v4
	ds_swizzle_b32 v5, v2 offset:swizzle(SWAP,16)
	s_waitcnt lgkmcnt(0)
	v_or_b32_e32 v2, v5, v2
	ds_swizzle_b32 v5, v4 offset:swizzle(SWAP,16)
	v_readfirstlane_b32 s20, v2
	s_waitcnt lgkmcnt(0)
	v_or_b32_e32 v4, v5, v4
	s_nop 0
	v_readfirstlane_b32 s21, v4
	v_mov_b32_e32 v5, v102
	v_mov_b32_e32 v4, v118
	s_waitcnt vmcnt(0) lgkmcnt(0)
	s_barrier
	s_cbranch_scc0 .LBB0_681
	s_flbit_i32_b64 s5, s[16:17]
	s_xor_b32 s5, s5, 63
	s_lshl_b64 s[24:25], 1, s5
	s_lshl_b32 s5, s5, 1
	s_or_b32 s11, s5, 1
	s_andn2_b64 s[24:25], s[16:17], s[24:25]
	s_lshl_b32 s13, s11, 5
	s_cmp_gt_i32 s13, s4
	s_cselect_b32 s13, -1, s5
	s_cselect_b32 s18, s5, s11

; __device__ __forceinline__ unsigned xb_xcc_id() { return (unsigned)__builtin_amdgcn_s_getreg((3 << 11) | 20) & 0xFu; }
; #define ARG_IN(i) ((const float*)karg64(8 * (i)))
; #define ARG_WS() ((unsigned char*)karg64(8 * 19))
; template <int ATTM> __device__ __forceinline__ void attention_phase(int layer, int lane, int rep, LAS unsigned char* lds, int wave) {
;     ...
;     if ((ATTM & 2) && PK(2)) {
; #pragma unroll 1
;         for (int qq = 0; qq < 8; ++qq) { const int q = ((int)(xb_xcc_id() & 7u) + qq) & 7;
;             for (;;) { WG_DRAW(0, q); if (it >= 32) break;
;                 unsigned char* ws = ARG_WS(); int tid = threadIdx.x; asm volatile("" : "+v"(tid));
;                 const float* lamv = ARG_IN(A_LAM) + (size_t)layer * 4 * 64;
;                 const float lam_init = 0.8f - 0.6f * __builtin_amdgcn_exp2f(-0.3f * 1.4426950408889634f * (float)layer);
;                 const float sa = wave_sum(lamv[lane] * lamv[64 + lane]), sb = wave_sum(lamv[128 + lane] * lamv[192 + lane]);
;                 const float lam = __builtin_amdgcn_exp2f(1.4426950408889634f * sa) - __builtin_amdgcn_exp2f(1.4426950408889634f * sb) + lam_init;
;                 dif_coop(WSP(bf16, WS_PROJ), ws + WS_VTB, WSP(bf16, WS_O), lam, ARG_IN(A_SUBG) + (size_t)layer * 128, 1.f - lam_init, q, 31 - it, lds, tid); } } }
;     if ((ATTM & 1) && PK(1)) {
; #pragma unroll 1
;         for (int qq = 0; qq < 8; ++qq) { const int q = ((int)(xb_xcc_id() & 7u) + qq) & 7; const int two = q + 8 < BATCH * 7 ? 1 : 0;
;             for (;;) { WG_DRAW(1, q); if (it >= (two ? 32 : 16)) break;
;                 unsigned char* ws = ARG_WS(); int tid = threadIdx.x; asm volatile("" : "+v"(tid));
;                 const int bh = two ? ((it & 1) ? q + 8 : q) : q, c = 15 - (two ? (it >> 1) : it);
;                 fox_coop(WSP(bf16, WS_PROJ), WSP(float, WS_CUM), ws + WS_VTB, WSP(bf16, WS_O), bh, c, lds, tid); } } }
;     if ((ATTM & 4) && PK(4)) {
; #pragma unroll 1
;         for (int qq = 0; qq < 8; ++qq) { const int q = ((int)(xb_xcc_id() & 7u) + qq) & 7;
;             for (;;) { WG_DRAW(2, q); if (it >= 32) break; unsigned char* ws = ARG_WS();
;                 nsa_quad_item(WSP(bf16, WS_PROJ), WSP(bf16, WS_KC), ws + WS_VCB, ws + WS_VTB, WSP(unsigned long long, WS_SEL), WSP(bf16, WS_O), lds, q >> 1, 2 * (31 - it) + (q & 1), wave); } } }
;     ...
;     if ((ATTM & 8) && PK(8)) {
.LBB0_749:
	s_cmp_lg_u32 s101, 0
	s_cbranch_scc1 .Lmy_p2_done
	s_mov_b32 s101, 1
	v_readlane_b32 s72, v255, 16
	v_readlane_b32 s73, v255, 17
	s_nop 4
	s_branch .Lmy_att_preamble
